# phase 5 role assignment: blocks 256-319 (co-resident with the scan blocks) swap roles with blocks 448-511, so the per-token wkv_direct units no longer share a CU with the sequential scan
# baseline (speedup 1.0000x reference)
.LBB0_796:
	s_setprio 2
	s_sub_i32 s3, s94, 64
	s_sub_i32 s10, s2, 64
	s_sub_i32 s0, s10, 0xc0
	s_cmp_lt_u32 s0, 64
	s_cbranch_scc0 .Lpm_a
	s_add_i32 s10, s10, 0xc0
	s_branch .Lpm_d
.Lpm_a:
	s_sub_i32 s0, s10, 0x180
	s_cmp_lt_u32 s0, 64
	s_cbranch_scc0 .Lpm_d
	s_sub_i32 s10, s10, 0xc0
.Lpm_d:
	s_cmpk_gt_i32 s10, 0xff
	s_cbranch_scc1 .LBB0_811
	v_mbcnt_lo_u32_b32 v0, -1, 0
	v_mbcnt_hi_u32_b32 v0, -1, v0
	v_and_b32_e32 v1, 64, v0
	v_add_u32_e32 v1, 64, v1
	v_xor_b32_e32 v2, 32, v0
	v_cmp_lt_i32_e32 vcc, v2, v1
	v_mul_u32_u24_e32 v212, 0x500, v214
	v_and_b32_e32 v188, 63, v218
	v_cndmask_b32_e32 v2, v0, v2, vcc
	v_lshlrev_b32_e32 v213, 2, v2
	v_xor_b32_e32 v2, 16, v0
	v_cmp_lt_i32_e32 vcc, v2, v1
	s_add_u32 s6, s84, 0x1080000
	v_or_b32_e32 v189, 64, v214
	v_cndmask_b32_e32 v2, v0, v2, vcc
	v_lshlrev_b32_e32 v215, 2, v2
	v_xor_b32_e32 v2, 8, v0
	v_cmp_lt_i32_e32 vcc, v2, v1
	v_mov_b32_e32 v191, 0
	v_lshl_or_b32 v221, v188, 2, v212
	v_cndmask_b32_e32 v2, v0, v2, vcc
	v_lshlrev_b32_e32 v216, 2, v2
	v_xor_b32_e32 v2, 4, v0
	v_cmp_lt_i32_e32 vcc, v2, v1
	s_addc_u32 s7, s85, 0
	v_mov_b32_e32 v222, 0x260
	v_cndmask_b32_e32 v2, v0, v2, vcc
	v_lshlrev_b32_e32 v217, 2, v2
	v_xor_b32_e32 v2, 2, v0
	v_cmp_lt_i32_e32 vcc, v2, v1
	v_mov_b32_e32 v223, 0x3a27c5ac
	v_mov_b32_e32 v224, 0x4000
	v_cndmask_b32_e32 v2, v0, v2, vcc
	v_lshlrev_b32_e32 v219, 2, v2
	v_xor_b32_e32 v2, 1, v0
	v_cmp_lt_i32_e32 vcc, v2, v1
	v_mov_b32_e32 v193, 1.0
	v_mov_b32_e32 v225, 0x442a000
	v_cndmask_b32_e32 v0, v0, v2, vcc
	v_lshlrev_b32_e32 v220, 2, v0
	v_mov_b32_e32 v226, 0x420e000
	s_mov_b32 s11, s10
